# band item epilogue: the eight gate loads issued together with counted waits instead of one vmcnt(0) per load
# speedup vs baseline: 1.0084x; 1.0084x over previous
; DI unsigned pack2(float a, float b) { f2_t v = {a, b}; bf2_t r = __builtin_convertvector(v, bf2_t); return __builtin_bit_cast(unsigned, r); }
; #define BLO(u) __uint_as_float((u) << 16)
; #define BHI(u) __uint_as_float((u) & 0xffff0000u)
; DI float frcp(float x) { return __builtin_amdgcn_rcpf(x); }
; template <int W, bool SINK>
; DI void attn_band_mfma(const bf16_t* Qb, size_t ldq, const bf16_t* Kb, const bf16_t* Vb, size_t ldk, int L, int i0,
;                        const float* lut_g, float sink2, bf16_t* outp, size_t ldo, float* lse_out, size_t ldl, char* smem) {
;     ...
;   const float ltot = half_swap_sum(l_run);
;   const float inv = frcp(ltot);
;   bf16_t* orow = outp + (size_t)qi * ldo;
;   if (!SINK && h == 0) lse_out[(size_t)qi * ldl] = m_run + __log2f(ltot);
; #pragma unroll
;   for (int db = 0; db < 2; ++db)
; #pragma unroll
;     for (int kp = 0; kp < 2; ++kp) {
;       uint2 w2[2];
; #pragma unroll
;       for (int gg = 0; gg < 2; ++gg) {
;         const int g4 = 2 * kp + gg;
;         float y[4];
;         if (SINK) {
;           uint2 u = *(const uint2*)(orow + 32 * db + 8 * g4 + 4 * h);
;           float g[4] = {BLO(u.x), BHI(u.x), BLO(u.y), BHI(u.y)};
; #pragma unroll
;           for (int e = 0; e < 4; ++e) { float ov = db == 0 ? o0[4 * g4 + e] : o1[4 * g4 + e]; y[e] = ov * inv * g[e] * frcp(1.0f + __expf(-g[e])); }
;         } else {
; #pragma unroll
;           for (int e = 0; e < 4; ++e) { float ov = db == 0 ? o0[4 * g4 + e] : o1[4 * g4 + e]; y[e] = ov * inv; }
;         }
;         w2[gg].x = pack2(y[0], y[1]); w2[gg].y = pack2(y[2], y[3]);
;       }
;       auto rx = __builtin_amdgcn_permlane32_swap(w2[0].x, w2[1].x, false, false);
;       auto ry = __builtin_amdgcn_permlane32_swap(w2[0].y, w2[1].y, false, false);
;       uint4 w; w.x = rx[0]; w.y = ry[0]; w.z = rx[1]; w.w = ry[1];
;       *(uint4*)(orow + 32 * db + 16 * kp + 8 * h) = w;
;     }
.LBB0_108:
	v_mov_b32_e32 v0, v138
	s_lshl_b32 s0, s30, 1
	s_nop 0
	v_permlane32_swap_b32_e32 v138, v0
	s_add_u32 s0, s28, s0
	v_add_f32_e32 v0, v138, v0
	s_addc_u32 s1, s29, 0
	v_rcp_f32_e32 v4, v0
	v_lshlrev_b32_e32 v0, 1, v132
	v_lshl_add_u64 v[2:3], s[0:1], 0, v[0:1]
	s_mov_b64 s[0:1], 0x2000
	v_lshl_add_u64 v[6:7], v[2:3], 0, s[0:1]
	v_lshlrev_b32_e32 v0, 1, v133
	v_lshl_add_u64 v[2:3], v[6:7], 0, v[0:1]
	v_lshlrev_b32_e32 v0, 1, v130
	v_lshl_add_u64 v[130:131], v[6:7], 0, v[0:1]
	global_load_dwordx2 v[98:99], v[2:3], off
	global_load_dwordx2 v[100:101], v[2:3], off offset:16
	global_load_dwordx2 v[102:103], v[2:3], off offset:32
	global_load_dwordx2 v[104:105], v[2:3], off offset:48
	global_load_dwordx2 v[106:107], v[2:3], off offset:64
	global_load_dwordx2 v[108:109], v[2:3], off offset:80
	global_load_dwordx2 v[110:111], v[2:3], off offset:96
	global_load_dwordx2 v[112:113], v[2:3], off offset:112
	v_mul_f32_e32 v12, v32, v4
	v_mul_f32_e32 v13, v33, v4
	v_mul_f32_e32 v14, v36, v4
	v_mul_f32_e32 v15, v37, v4
	v_readlane_b32 s28, v255, 3
	s_mov_b64 s[0:1], 0
	v_readlane_b32 s29, v255, 4
	s_waitcnt vmcnt(7)
	v_mov_b32_e32 v6, v98
	v_mov_b32_e32 v7, v99
	v_lshlrev_b32_e32 v8, 16, v6
	v_mul_f32_e32 v0, 0xbfb8aa3b, v8
	v_exp_f32_e32 v0, v0
	v_and_b32_e32 v9, 0xffff0000, v6
	v_mul_f32_e32 v12, v12, v8
	v_mul_f32_e32 v13, v13, v9
	v_lshlrev_b32_e32 v6, 16, v7
	v_add_f32_e32 v0, 1.0, v0
	v_rcp_f32_e32 v10, v0
	v_mul_f32_e32 v0, 0xbfb8aa3b, v9
	v_exp_f32_e32 v0, v0
	v_and_b32_e32 v7, 0xffff0000, v7
	v_add_f32_e32 v0, 1.0, v0
	v_rcp_f32_e32 v11, v0
	v_mul_f32_e32 v0, 0xbfb8aa3b, v6
	v_exp_f32_e32 v0, v0
	v_mul_f32_e32 v8, v12, v10
	v_mul_f32_e32 v9, v13, v11
	v_mul_f32_e32 v12, v34, v4
	v_mul_f32_e32 v13, v35, v4
	v_add_f32_e32 v0, 1.0, v0
	v_mul_f32_e32 v12, v12, v6
	v_mul_f32_e32 v13, v13, v7
	v_cvt_pk_bf16_f32 v6, v8, v9
	v_rcp_f32_e32 v10, v0
	v_mul_f32_e32 v0, 0xbfb8aa3b, v7
	v_exp_f32_e32 v0, v0
	s_nop 0
	v_add_f32_e32 v0, 1.0, v0
	v_rcp_f32_e32 v11, v0
	s_nop 0
	v_mul_f32_e32 v10, v12, v10
	v_mul_f32_e32 v11, v13, v11
	s_nop 0
	v_cvt_pk_bf16_f32 v7, v10, v11
	s_waitcnt vmcnt(6)
	v_mov_b32_e32 v8, v100
	v_mov_b32_e32 v9, v101
	v_lshlrev_b32_e32 v10, 16, v8
	v_mul_f32_e32 v0, 0xbfb8aa3b, v10
	v_exp_f32_e32 v0, v0
	v_and_b32_e32 v11, 0xffff0000, v8
	v_lshlrev_b32_e32 v8, 16, v9
	v_and_b32_e32 v9, 0xffff0000, v9
	v_add_f32_e32 v0, 1.0, v0
	v_rcp_f32_e32 v12, v0
	v_mul_f32_e32 v0, 0xbfb8aa3b, v11
	v_exp_f32_e32 v0, v0
	v_mul_f32_e32 v14, v14, v10
	v_mul_f32_e32 v15, v15, v11
	v_add_f32_e32 v0, 1.0, v0
	v_rcp_f32_e32 v13, v0
	v_mul_f32_e32 v0, 0xbfb8aa3b, v8
	v_exp_f32_e32 v0, v0
	v_mul_f32_e32 v10, v14, v12
	v_mul_f32_e32 v11, v15, v13
	v_mul_f32_e32 v14, v38, v4
	v_mul_f32_e32 v15, v39, v4
	v_add_f32_e32 v0, 1.0, v0
	v_rcp_f32_e32 v12, v0
	v_mul_f32_e32 v0, 0xbfb8aa3b, v9
	v_exp_f32_e32 v0, v0
	v_mul_f32_e32 v14, v14, v8
	v_mul_f32_e32 v15, v15, v9
	v_cvt_pk_bf16_f32 v8, v10, v11
	s_nop 1
	v_permlane32_swap_b32_e32 v6, v8
	v_add_f32_e32 v0, 1.0, v0
	v_rcp_f32_e32 v13, v0
	s_nop 0
	v_mul_f32_e32 v12, v14, v12
	v_mul_f32_e32 v13, v15, v13
	s_nop 0
	v_cvt_pk_bf16_f32 v9, v12, v13
	s_nop 1
	v_permlane32_swap_b32_e32 v7, v9
	global_store_dwordx4 v[130:131], v[6:9], off
	v_mul_f32_e32 v12, v40, v4
	v_mul_f32_e32 v13, v41, v4
	v_mul_f32_e32 v14, v44, v4
	v_mul_f32_e32 v15, v45, v4
	s_waitcnt vmcnt(6)
	v_mov_b32_e32 v6, v102
	v_mov_b32_e32 v7, v103
	v_lshlrev_b32_e32 v8, 16, v6
	v_mul_f32_e32 v0, 0xbfb8aa3b, v8
	v_exp_f32_e32 v0, v0
	v_and_b32_e32 v9, 0xffff0000, v6
	v_mul_f32_e32 v12, v12, v8
	v_mul_f32_e32 v13, v13, v9
	v_lshlrev_b32_e32 v6, 16, v7
	v_add_f32_e32 v0, 1.0, v0
	v_rcp_f32_e32 v10, v0
	v_mul_f32_e32 v0, 0xbfb8aa3b, v9
	v_exp_f32_e32 v0, v0
	v_and_b32_e32 v7, 0xffff0000, v7
	v_add_f32_e32 v0, 1.0, v0
	v_rcp_f32_e32 v11, v0
	v_mul_f32_e32 v0, 0xbfb8aa3b, v6
	v_exp_f32_e32 v0, v0
	v_mul_f32_e32 v8, v12, v10
	v_mul_f32_e32 v9, v13, v11
	v_mul_f32_e32 v12, v42, v4
	v_mul_f32_e32 v13, v43, v4
	v_add_f32_e32 v0, 1.0, v0
	v_mul_f32_e32 v12, v12, v6
	v_mul_f32_e32 v13, v13, v7
	v_cvt_pk_bf16_f32 v6, v8, v9
	v_rcp_f32_e32 v10, v0
	v_mul_f32_e32 v0, 0xbfb8aa3b, v7
	v_exp_f32_e32 v0, v0
	s_nop 0
	v_add_f32_e32 v0, 1.0, v0
	v_rcp_f32_e32 v11, v0
	s_nop 0
	v_mul_f32_e32 v10, v12, v10
	v_mul_f32_e32 v11, v13, v11
	s_nop 0
	v_cvt_pk_bf16_f32 v7, v10, v11
	s_waitcnt vmcnt(5)
; DI unsigned pack2(float a, float b) { f2_t v = {a, b}; bf2_t r = __builtin_convertvector(v, bf2_t); return __builtin_bit_cast(unsigned, r); }
; #define BLO(u) __uint_as_float((u) << 16)
; #define BHI(u) __uint_as_float((u) & 0xffff0000u)
; DI float frcp(float x) { return __builtin_amdgcn_rcpf(x); }
; template <int W, bool SINK>
; DI void attn_band_mfma(const bf16_t* Qb, size_t ldq, const bf16_t* Kb, const bf16_t* Vb, size_t ldk, int L, int i0,
;                        const float* lut_g, float sink2, bf16_t* outp, size_t ldo, float* lse_out, size_t ldl, char* smem) {
;     ...
; #pragma unroll
;   for (int db = 0; db < 2; ++db)
; #pragma unroll
;     for (int kp = 0; kp < 2; ++kp) {
;       uint2 w2[2];
; #pragma unroll
;       for (int gg = 0; gg < 2; ++gg) {
;         const int g4 = 2 * kp + gg;
;         float y[4];
;         if (SINK) {
;           uint2 u = *(const uint2*)(orow + 32 * db + 8 * g4 + 4 * h);
;           float g[4] = {BLO(u.x), BHI(u.x), BLO(u.y), BHI(u.y)};
; #pragma unroll
;           for (int e = 0; e < 4; ++e) { float ov = db == 0 ? o0[4 * g4 + e] : o1[4 * g4 + e]; y[e] = ov * inv * g[e] * frcp(1.0f + __expf(-g[e])); }
;         } else {
; #pragma unroll
;           for (int e = 0; e < 4; ++e) { float ov = db == 0 ? o0[4 * g4 + e] : o1[4 * g4 + e]; y[e] = ov * inv; }
;         }
;         w2[gg].x = pack2(y[0], y[1]); w2[gg].y = pack2(y[2], y[3]);
;       }
;       auto rx = __builtin_amdgcn_permlane32_swap(w2[0].x, w2[1].x, false, false);
;       auto ry = __builtin_amdgcn_permlane32_swap(w2[0].y, w2[1].y, false, false);
;       uint4 w; w.x = rx[0]; w.y = ry[0]; w.z = rx[1]; w.w = ry[1];
;       *(uint4*)(orow + 32 * db + 16 * kp + 8 * h) = w;
;     }
	v_mov_b32_e32 v8, v104
	v_mov_b32_e32 v9, v105
	v_lshlrev_b32_e32 v10, 16, v8
	v_mul_f32_e32 v0, 0xbfb8aa3b, v10
	v_exp_f32_e32 v0, v0
	v_and_b32_e32 v11, 0xffff0000, v8
	v_lshlrev_b32_e32 v8, 16, v9
	v_and_b32_e32 v9, 0xffff0000, v9
	v_add_f32_e32 v0, 1.0, v0
	v_rcp_f32_e32 v12, v0
	v_mul_f32_e32 v0, 0xbfb8aa3b, v11
	v_exp_f32_e32 v0, v0
	v_mul_f32_e32 v14, v14, v10
	v_mul_f32_e32 v15, v15, v11
	v_add_f32_e32 v0, 1.0, v0
	v_rcp_f32_e32 v13, v0
	v_mul_f32_e32 v0, 0xbfb8aa3b, v8
	v_exp_f32_e32 v0, v0
	v_mul_f32_e32 v10, v14, v12
	v_mul_f32_e32 v11, v15, v13
	v_mul_f32_e32 v14, v46, v4
	v_mul_f32_e32 v15, v47, v4
	v_add_f32_e32 v0, 1.0, v0
	v_rcp_f32_e32 v12, v0
	v_mul_f32_e32 v0, 0xbfb8aa3b, v9
	v_exp_f32_e32 v0, v0
	v_mul_f32_e32 v14, v14, v8
	v_mul_f32_e32 v15, v15, v9
	v_cvt_pk_bf16_f32 v8, v10, v11
	s_nop 1
	v_permlane32_swap_b32_e32 v6, v8
	v_add_f32_e32 v0, 1.0, v0
	v_rcp_f32_e32 v13, v0
	s_nop 0
	v_mul_f32_e32 v12, v14, v12
	v_mul_f32_e32 v13, v15, v13
	s_nop 0
	v_cvt_pk_bf16_f32 v9, v12, v13
	s_nop 1
	v_permlane32_swap_b32_e32 v7, v9
	global_store_dwordx4 v[130:131], v[6:9], off offset:32
	v_mul_f32_e32 v12, v16, v4
	v_mul_f32_e32 v13, v17, v4
	v_mul_f32_e32 v14, v20, v4
	v_mul_f32_e32 v15, v21, v4
	s_waitcnt vmcnt(5)
	v_mov_b32_e32 v6, v106
	v_mov_b32_e32 v7, v107
	v_lshlrev_b32_e32 v8, 16, v6
	v_mul_f32_e32 v0, 0xbfb8aa3b, v8
	v_exp_f32_e32 v0, v0
	v_and_b32_e32 v9, 0xffff0000, v6
	v_mul_f32_e32 v12, v12, v8
	v_mul_f32_e32 v13, v13, v9
	v_lshlrev_b32_e32 v6, 16, v7
	v_add_f32_e32 v0, 1.0, v0
	v_rcp_f32_e32 v10, v0
	v_mul_f32_e32 v0, 0xbfb8aa3b, v9
	v_exp_f32_e32 v0, v0
	v_and_b32_e32 v7, 0xffff0000, v7
	v_add_f32_e32 v0, 1.0, v0
	v_rcp_f32_e32 v11, v0
	v_mul_f32_e32 v0, 0xbfb8aa3b, v6
	v_exp_f32_e32 v0, v0
	v_mul_f32_e32 v8, v12, v10
	v_mul_f32_e32 v9, v13, v11
	v_mul_f32_e32 v12, v18, v4
	v_mul_f32_e32 v13, v19, v4
	v_add_f32_e32 v0, 1.0, v0
	v_mul_f32_e32 v12, v12, v6
	v_mul_f32_e32 v13, v13, v7
	v_cvt_pk_bf16_f32 v6, v8, v9
	v_rcp_f32_e32 v10, v0
	v_mul_f32_e32 v0, 0xbfb8aa3b, v7
	v_exp_f32_e32 v0, v0
	s_nop 0
	v_add_f32_e32 v0, 1.0, v0
	v_rcp_f32_e32 v11, v0
	s_nop 0
	v_mul_f32_e32 v10, v12, v10
	v_mul_f32_e32 v11, v13, v11
	s_nop 0
	v_cvt_pk_bf16_f32 v7, v10, v11
	s_waitcnt vmcnt(4)
	v_mov_b32_e32 v8, v108
	v_mov_b32_e32 v9, v109
	v_lshlrev_b32_e32 v10, 16, v8
	v_mul_f32_e32 v0, 0xbfb8aa3b, v10
	v_exp_f32_e32 v0, v0
	v_and_b32_e32 v11, 0xffff0000, v8
	v_lshlrev_b32_e32 v8, 16, v9
	v_and_b32_e32 v9, 0xffff0000, v9
	v_add_f32_e32 v0, 1.0, v0
	v_rcp_f32_e32 v12, v0
	v_mul_f32_e32 v0, 0xbfb8aa3b, v11
	v_exp_f32_e32 v0, v0
	v_mul_f32_e32 v14, v14, v10
	v_mul_f32_e32 v15, v15, v11
	v_add_f32_e32 v0, 1.0, v0
	v_rcp_f32_e32 v13, v0
	v_mul_f32_e32 v0, 0xbfb8aa3b, v8
	v_exp_f32_e32 v0, v0
	v_mul_f32_e32 v10, v14, v12
	v_mul_f32_e32 v11, v15, v13
	v_mul_f32_e32 v14, v22, v4
	v_mul_f32_e32 v15, v23, v4
	v_add_f32_e32 v0, 1.0, v0
	v_rcp_f32_e32 v12, v0
	v_mul_f32_e32 v0, 0xbfb8aa3b, v9
	v_exp_f32_e32 v0, v0
	v_mul_f32_e32 v14, v14, v8
	v_mul_f32_e32 v15, v15, v9
	v_cvt_pk_bf16_f32 v8, v10, v11
	s_nop 1
	v_permlane32_swap_b32_e32 v6, v8
	v_add_f32_e32 v0, 1.0, v0
	v_rcp_f32_e32 v13, v0
	s_nop 0
	v_mul_f32_e32 v12, v14, v12
	v_mul_f32_e32 v13, v15, v13
	s_nop 0
	v_cvt_pk_bf16_f32 v9, v12, v13
	s_nop 1
	v_permlane32_swap_b32_e32 v7, v9
	global_store_dwordx4 v[130:131], v[6:9], off offset:64
	s_nop 0
	v_mul_f32_e32 v14, v28, v4
	v_mul_f32_e32 v15, v29, v4
	s_waitcnt vmcnt(3)
	v_mov_b32_e32 v6, v110
	v_mov_b32_e32 v7, v111
	v_mov_b32_e32 v2, v112
	v_mov_b32_e32 v3, v113
	v_and_b32_e32 v11, 0xffff0000, v2
	v_mul_f32_e32 v0, 0xbfb8aa3b, v11
	v_exp_f32_e32 v0, v0
	v_lshlrev_b32_e32 v10, 16, v2
	v_lshlrev_b32_e32 v2, 16, v7
	v_lshlrev_b32_e32 v8, 16, v3
	v_add_f32_e32 v0, 1.0, v0
	v_rcp_f32_e32 v13, v0
	v_mul_f32_e32 v0, 0xbfb8aa3b, v10
	v_exp_f32_e32 v0, v0
	v_mul_f32_e32 v14, v14, v10
	v_mul_f32_e32 v15, v15, v11
	v_and_b32_e32 v9, 0xffff0000, v3
	v_and_b32_e32 v3, 0xffff0000, v7
	v_add_f32_e32 v0, 1.0, v0
	v_rcp_f32_e32 v12, v0
	v_mul_f32_e32 v0, 0xbfb8aa3b, v2
	v_exp_f32_e32 v0, v0
	v_mul_f32_e32 v10, v14, v12
	v_mul_f32_e32 v11, v15, v13
	v_mul_f32_e32 v14, v26, v4
	v_mul_f32_e32 v15, v27, v4
	v_add_f32_e32 v0, 1.0, v0
	v_rcp_f32_e32 v12, v0
	v_mul_f32_e32 v0, 0xbfb8aa3b, v3
	v_exp_f32_e32 v0, v0
	v_mul_f32_e32 v14, v14, v2
	v_mul_f32_e32 v15, v15, v3
	v_add_f32_e32 v0, 1.0, v0
	v_rcp_f32_e32 v13, v0
	s_nop 0
	v_mul_f32_e32 v2, v14, v12
	v_mul_f32_e32 v3, v15, v13
	v_lshlrev_b32_e32 v12, 16, v6
	v_mul_f32_e32 v0, 0xbfb8aa3b, v12
	v_exp_f32_e32 v0, v0
	v_and_b32_e32 v13, 0xffff0000, v6
	v_cvt_pk_bf16_f32 v2, v2, v3
	v_mul_f32_e32 v3, 0xbfb8aa3b, v8
	v_add_f32_e32 v0, 1.0, v0
	v_rcp_f32_e32 v6, v0
	v_mul_f32_e32 v0, 0xbfb8aa3b, v13
	v_exp_f32_e32 v0, v0
	v_exp_f32_e32 v3, v3
	v_mul_f32_e32 v14, v24, v4
	v_mul_f32_e32 v15, v25, v4
	v_mul_f32_e32 v5, v31, v4
	v_mul_f32_e32 v4, v30, v4
	v_add_f32_e32 v0, 1.0, v0
	v_rcp_f32_e32 v7, v0
	v_mul_f32_e32 v14, v14, v12
	v_mul_f32_e32 v15, v15, v13
	v_add_f32_e32 v3, 1.0, v3
	v_mul_f32_e32 v4, v4, v8
	v_mul_f32_e32 v5, v5, v9
	v_mul_f32_e32 v6, v14, v6
	v_mul_f32_e32 v7, v15, v7
	s_nop 0
	v_cvt_pk_bf16_f32 v0, v6, v7
	v_rcp_f32_e32 v6, v3
	v_mul_f32_e32 v3, 0xbfb8aa3b, v9
	v_exp_f32_e32 v3, v3
	s_nop 0
	v_add_f32_e32 v3, 1.0, v3
	v_rcp_f32_e32 v7, v3
	v_cvt_pk_bf16_f32 v3, v10, v11
	s_nop 1
	v_permlane32_swap_b32_e32 v0, v3
	v_mul_f32_e32 v4, v4, v6
	v_mul_f32_e32 v5, v5, v7
	global_store_dword v[130:131], v0, off offset:96
	v_cvt_pk_bf16_f32 v4, v4, v5
	s_nop 1
	v_permlane32_swap_b32_e32 v2, v4
